# MoBA gate: two kmean blocks per iteration, all 16 LDS reads issued up front, one permlane swap leaves block n in the low half and n+1 in the high half, halves' top-3 lists merged once
# baseline (speedup 1.0000x reference)
.LBB0_390:
	ds_read_b128 v[60:63], v54
	ds_read_b128 v[68:71], v54 offset:16
	ds_read_b128 v[72:75], v54 offset:64
	ds_read_b128 v[76:79], v54 offset:80
	ds_read_b128 v[80:83], v54 offset:128
	ds_read_b128 v[84:87], v54 offset:144
	ds_read_b128 v[88:91], v54 offset:192
	ds_read_b128 v[124:127], v54 offset:208
	ds_read_b128 v[92:95], v54 offset:256
	ds_read_b128 v[96:99], v54 offset:272
	ds_read_b128 v[100:103], v54 offset:320
	ds_read_b128 v[104:107], v54 offset:336
	ds_read_b128 v[108:111], v54 offset:384
	ds_read_b128 v[112:115], v54 offset:400
	ds_read_b128 v[116:119], v54 offset:448
	ds_read_b128 v[120:123], v54 offset:464
	s_waitcnt lgkmcnt(15)
	v_pk_mul_f32 v[64:65], v[60:61], v[26:27]
	v_pk_fma_f32 v[64:65], v[62:63], v[28:29], v[64:65]
	s_waitcnt lgkmcnt(14)
	v_pk_fma_f32 v[64:65], v[68:69], v[30:31], v[64:65]
	v_pk_fma_f32 v[64:65], v[70:71], v[32:33], v[64:65]
	s_waitcnt lgkmcnt(13)
	v_pk_fma_f32 v[64:65], v[72:73], v[38:39], v[64:65]
	v_pk_fma_f32 v[64:65], v[74:75], v[40:41], v[64:65]
	s_waitcnt lgkmcnt(12)
	v_pk_fma_f32 v[64:65], v[76:77], v[42:43], v[64:65]
	v_pk_fma_f32 v[64:65], v[78:79], v[44:45], v[64:65]
	s_waitcnt lgkmcnt(11)
	v_pk_fma_f32 v[64:65], v[80:81], v[46:47], v[64:65]
	v_pk_fma_f32 v[64:65], v[82:83], v[48:49], v[64:65]
	s_waitcnt lgkmcnt(10)
	v_pk_fma_f32 v[64:65], v[84:85], v[50:51], v[64:65]
	v_pk_fma_f32 v[64:65], v[86:87], v[52:53], v[64:65]
	s_waitcnt lgkmcnt(9)
	v_pk_fma_f32 v[64:65], v[88:89], v[18:19], v[64:65]
	v_pk_fma_f32 v[64:65], v[90:91], v[20:21], v[64:65]
	s_waitcnt lgkmcnt(8)
	v_pk_fma_f32 v[64:65], v[124:125], v[22:23], v[64:65]
	v_pk_fma_f32 v[64:65], v[126:127], v[24:25], v[64:65]
	s_waitcnt lgkmcnt(7)
	v_pk_mul_f32 v[128:129], v[92:93], v[26:27]
	v_pk_fma_f32 v[128:129], v[94:95], v[28:29], v[128:129]
	s_waitcnt lgkmcnt(6)
	v_pk_fma_f32 v[128:129], v[96:97], v[30:31], v[128:129]
	v_pk_fma_f32 v[128:129], v[98:99], v[32:33], v[128:129]
	s_waitcnt lgkmcnt(5)
	v_pk_fma_f32 v[128:129], v[100:101], v[38:39], v[128:129]
	v_pk_fma_f32 v[128:129], v[102:103], v[40:41], v[128:129]
	s_waitcnt lgkmcnt(4)
	v_pk_fma_f32 v[128:129], v[104:105], v[42:43], v[128:129]
	v_pk_fma_f32 v[128:129], v[106:107], v[44:45], v[128:129]
	s_waitcnt lgkmcnt(3)
	v_pk_fma_f32 v[128:129], v[108:109], v[46:47], v[128:129]
	v_pk_fma_f32 v[128:129], v[110:111], v[48:49], v[128:129]
	s_waitcnt lgkmcnt(2)
	v_pk_fma_f32 v[128:129], v[112:113], v[50:51], v[128:129]
	v_pk_fma_f32 v[128:129], v[114:115], v[52:53], v[128:129]
	s_waitcnt lgkmcnt(1)
	v_pk_fma_f32 v[128:129], v[116:117], v[18:19], v[128:129]
	v_pk_fma_f32 v[128:129], v[118:119], v[20:21], v[128:129]
	s_waitcnt lgkmcnt(0)
	v_pk_fma_f32 v[128:129], v[120:121], v[22:23], v[128:129]
	v_pk_fma_f32 v[128:129], v[122:123], v[24:25], v[128:129]
	v_add_f32_e32 v36, v64, v65
	v_add_f32_e32 v37, v128, v129
	s_lshl_b32 s50, 1, s49
	s_add_i32 s49, s49, 2
	s_nop 0
	v_permlane32_swap_b32_e32 v36, v37
	v_add_u32_e32 v54, 0x200, v54
	v_add_f32_e32 v60, v36, v37
	s_cmp_gt_u32 s49, s82
	s_cbranch_scc0 .Lgate2_ok
	s_mov_b32 exec_lo, 0
	v_mov_b32_e32 v60, 0xff800000
	s_mov_b32 exec_lo, -1
.Lgate2_ok:
	v_lshlrev_b32_e64 v37, v211, s50
	v_cmp_gt_f32_e64 s[8:9], v60, v55
	v_cmp_gt_f32_e64 s[42:43], v60, v56
	v_cmp_gt_f32_e32 vcc, v60, v59
	v_cndmask_b32_e32 v35, v35, v37, vcc
	v_med3_f32 v59, v60, v56, v59
	v_cndmask_b32_e64 v35, v35, v57, s[42:43]
	v_cndmask_b32_e64 v57, v57, v37, s[42:43]
	v_med3_f32 v56, v60, v55, v56
	v_cndmask_b32_e64 v57, v57, v58, s[8:9]
	v_cndmask_b32_e64 v58, v58, v37, s[8:9]
	v_max_f32_e32 v55, v55, v60
	s_cmp_lt_u32 s49, s82
	s_cbranch_scc1 .LBB0_390
	v_mov_b32_e32 v86, v55
	v_mov_b32_e32 v87, v56
	v_mov_b32_e32 v88, v59
	v_mov_b32_e32 v89, v58
	v_mov_b32_e32 v90, v57
	v_mov_b32_e32 v91, v35
	s_nop 1
	v_permlane32_swap_b32_e32 v55, v86
	v_permlane32_swap_b32_e32 v56, v87
	v_permlane32_swap_b32_e32 v59, v88
	v_permlane32_swap_b32_e32 v58, v89
	v_permlane32_swap_b32_e32 v57, v90
	v_permlane32_swap_b32_e32 v35, v91
	v_cmp_gt_f32_e64 s[8:9], v86, v55
	v_cmp_gt_f32_e64 s[42:43], v86, v56
	v_cmp_gt_f32_e32 vcc, v86, v59
	v_cndmask_b32_e32 v35, v35, v89, vcc
	v_med3_f32 v59, v86, v56, v59
	v_cndmask_b32_e64 v35, v35, v57, s[42:43]
	v_cndmask_b32_e64 v57, v57, v89, s[42:43]
	v_med3_f32 v56, v86, v55, v56
	v_cndmask_b32_e64 v57, v57, v58, s[8:9]
	v_cndmask_b32_e64 v58, v58, v89, s[8:9]
	v_max_f32_e32 v55, v55, v86
	v_cmp_gt_f32_e64 s[8:9], v87, v55
	v_cmp_gt_f32_e64 s[42:43], v87, v56
	v_cmp_gt_f32_e32 vcc, v87, v59
	v_cndmask_b32_e32 v35, v35, v90, vcc
	v_med3_f32 v59, v87, v56, v59
	v_cndmask_b32_e64 v35, v35, v57, s[42:43]
	v_cndmask_b32_e64 v57, v57, v90, s[42:43]
	v_med3_f32 v56, v87, v55, v56
	v_cndmask_b32_e64 v57, v57, v58, s[8:9]
	v_cndmask_b32_e64 v58, v58, v90, s[8:9]
	v_max_f32_e32 v55, v55, v87
	v_cmp_gt_f32_e64 s[8:9], v88, v55
	v_cmp_gt_f32_e64 s[42:43], v88, v56
	v_cmp_gt_f32_e32 vcc, v88, v59
	v_cndmask_b32_e32 v35, v35, v91, vcc
	v_med3_f32 v59, v88, v56, v59
	v_cndmask_b32_e64 v35, v35, v57, s[42:43]
	v_cndmask_b32_e64 v57, v57, v91, s[42:43]
	v_med3_f32 v56, v88, v55, v56
	v_cndmask_b32_e64 v57, v57, v58, s[8:9]
	v_cndmask_b32_e64 v58, v58, v91, s[8:9]
	v_max_f32_e32 v55, v55, v88
	v_mov_b32_e32 v37, v58
	v_mov_b32_e32 v36, v57
	s_branch .LBB0_400
